# hand-written sliding-window loop: running max folded into the MFMA C operand, packed max tree, in-place accumulators
# baseline (speedup 1.0000x reference)
; #define LAS __attribute__((address_space(3)))
; __device__ __forceinline__ float bf1(bf16_t u) { return __uint_as_float(((unsigned)u) << 16); }
; __device__ __forceinline__ float sigm(float x) { return rcpf_(1.f + ex2(-1.44269504f * x)); }
; #define LDS_WAIT() asm volatile("s_waitcnt lgkmcnt(0)" ::: "memory")
; __device__ __forceinline__ float xq_sum(float v) { const auto r = __builtin_amdgcn_permlane16_swap(__float_as_uint(v), __float_as_uint(v), false, false); return xhalf_sum(__uint_as_float(r[0]) + __uint_as_float(r[1])); }
; __device__ __forceinline__ void nsa_tile(const Ctx& C, int b, int g, int t0) {
;     ...
;             gs4[sub] = sigm(bf1(P[tok4 * PP + PC_NG + head4 * 3 + 1]));
;         }
;         float ma = -1e30f, la = 0.f, mb = -1e30f, lb = 0.f; f32x4v Oa[4], Ob[4];
; #pragma unroll
;         for (int dt = 0; dt < 4; ++dt) { Oa[dt] = (f32x4v){0.f, 0.f, 0.f, 0.f}; Ob[dt] = (f32x4v){0.f, 0.f, 0.f, 0.f}; }
;         flash16_run(kb, vb, q16f[0], q16f[1], 2 * nblk, list, tq, t0, qi4, fq, ma, la, Oa, mb, lb, Ob);
;         la = xq_sum(la); lb = xq_sum(lb);
;         const float sca = gs4[0] / fmaxf(la, 1e-30f), scb = gs4[1] / fmaxf(lb, 1e-30f);
; #pragma unroll
;         for (int dt = 0; dt < 4; ++dt)
; #pragma unroll
;             for (int i = 0; i < 4; ++i) { LAS float* op = ostb + ((dt >> 1) * 16 + 4 * (2 * (dt & 1) + (fq >> 1)) + i) * 64 + q16 + 32 * (fq & 1); op[0] += sca * Oa[dt][i]; op[16] += scb * Ob[dt][i]; }
;         LDS_WAIT();
.LBB0_866:
	s_waitcnt vmcnt(1)
	v_lshlrev_b32_e32 v3, 16, v251
	v_mul_f32_e32 v3, 0xbfb8aa3b, v3
	v_mov_b32_e32 v5, v238
	v_exp_f32_e32 v3, v3
	s_nop 0
	v_permlane16_swap_b32_e32 v238, v5
	v_add_f32_e32 v5, v238, v5
	v_mov_b32_e32 v6, v5
	s_nop 1
	v_permlane32_swap_b32_e32 v5, v6
	v_add_f32_e32 v3, 1.0, v3
	v_add_f32_e32 v5, v5, v6
	v_mov_b32_e32 v6, v239
	v_rcp_f32_e32 v3, v3
	s_nop 0
	v_permlane16_swap_b32_e32 v239, v6
	v_add_f32_e32 v6, v239, v6
	v_mov_b32_e32 v7, v6
	s_nop 1
	v_permlane32_swap_b32_e32 v6, v7
	v_max_f32_e32 v5, 0xda24260, v5
	v_add_f32_e32 v6, v6, v7
	v_div_scale_f32 v7, s[0:1], v5, v5, v3
	v_rcp_f32_e32 v8, v7
	s_waitcnt vmcnt(0)
	v_lshlrev_b32_e32 v4, 16, v210
	v_mul_f32_e32 v4, 0xbfb8aa3b, v4
	v_exp_f32_e32 v4, v4
	v_fma_f32 v9, -v7, v8, 1.0
	v_fmac_f32_e32 v8, v9, v8
	v_div_scale_f32 v9, vcc, v3, v5, v3
	v_mul_f32_e32 v10, v9, v8
	v_add_f32_e32 v4, 1.0, v4
	v_fma_f32 v11, -v7, v10, v9
	v_rcp_f32_e32 v4, v4
	v_fmac_f32_e32 v10, v11, v8
	v_fma_f32 v7, -v7, v10, v9
	v_div_fmas_f32 v7, v7, v8, v10
	v_div_fixup_f32 v5, v7, v5, v3
	v_max_f32_e32 v3, 0xda24260, v6
	v_div_scale_f32 v6, s[0:1], v3, v3, v4
	v_rcp_f32_e32 v7, v6
	v_and_b32_e32 v2, 15, v224
	v_lshl_add_u32 v2, v2, 2, s73
	s_max_i32 s1, s97, 0x1ff
	v_fma_f32 v8, -v6, v7, 1.0
	v_fmac_f32_e32 v7, v8, v7
	v_div_scale_f32 v8, vcc, v4, v3, v4
	v_mul_f32_e32 v9, v8, v7
	v_fma_f32 v10, -v6, v9, v8
	v_fmac_f32_e32 v9, v10, v7
	v_fma_f32 v6, -v6, v9, v8
	v_div_fmas_f32 v6, v6, v7, v9
	v_div_fixup_f32 v4, v6, v3, v4
	v_lshlrev_b32_e32 v3, 7, v245
	v_and_b32_e32 v3, 0x80, v3
	v_lshlrev_b32_e32 v6, 10, v244
	v_add3_u32 v6, v2, v3, v6
	v_add_u32_e32 v7, 0x2000, v6
	ds_read2_b32 v[2:3], v7 offset0:64 offset1:80
	s_addk_i32 s1, 0xfe01
	s_lshr_b32 s0, s1, 5
	s_lshr_b32 s4, s97, 5
	s_sub_i32 s2, s4, s0
	s_waitcnt lgkmcnt(0)
	v_fma_f32 v2, v34, v5, v2
	v_fmac_f32_e32 v3, v18, v4
	ds_write2_b32 v7, v2, v3 offset0:64 offset1:80
	ds_read2_b32 v[2:3], v7 offset0:128 offset1:144
	s_mov_b32 s3, 0
	s_cmp_lt_i32 s2, 0
	s_waitcnt lgkmcnt(0)
	v_fma_f32 v2, v35, v5, v2
	v_fmac_f32_e32 v3, v19, v4
	ds_write2_b32 v7, v2, v3 offset0:128 offset1:144
	ds_read2_b32 v[2:3], v7 offset0:192 offset1:208
	s_waitcnt lgkmcnt(0)
	v_fma_f32 v2, v36, v5, v2
	v_fmac_f32_e32 v3, v20, v4
	ds_write2_b32 v7, v2, v3 offset0:192 offset1:208
	v_add_u32_e32 v7, 0x2400, v6
	ds_read2_b32 v[2:3], v7 offset1:16
	s_waitcnt lgkmcnt(0)
	v_fma_f32 v2, v37, v5, v2
	v_fmac_f32_e32 v3, v21, v4
	ds_write2_b32 v7, v2, v3 offset1:16
	v_add_u32_e32 v7, 0x2800, v6
	ds_read2_b32 v[2:3], v7 offset0:64 offset1:80
	s_waitcnt lgkmcnt(0)
	v_fma_f32 v2, v38, v5, v2
	v_fmac_f32_e32 v3, v22, v4
	ds_write2_b32 v7, v2, v3 offset0:64 offset1:80
	ds_read2_b32 v[2:3], v7 offset0:128 offset1:144
	s_waitcnt lgkmcnt(0)
	v_fma_f32 v2, v39, v5, v2
	v_fmac_f32_e32 v3, v23, v4
	ds_write2_b32 v7, v2, v3 offset0:128 offset1:144
	ds_read2_b32 v[2:3], v7 offset0:192 offset1:208
	s_waitcnt lgkmcnt(0)
	v_fma_f32 v2, v40, v5, v2
	v_fmac_f32_e32 v3, v24, v4
	ds_write2_b32 v7, v2, v3 offset0:192 offset1:208
	v_add_u32_e32 v7, 0x2c00, v6
	ds_read2_b32 v[2:3], v7 offset1:16
	s_waitcnt lgkmcnt(0)
	v_fma_f32 v2, v41, v5, v2
	v_fmac_f32_e32 v3, v25, v4
	ds_write2_b32 v7, v2, v3 offset1:16
	v_add_u32_e32 v7, 0x3000, v6
	ds_read2_b32 v[2:3], v7 offset0:64 offset1:80
	s_waitcnt lgkmcnt(0)
	v_fma_f32 v2, v42, v5, v2
	v_fmac_f32_e32 v3, v26, v4
	ds_write2_b32 v7, v2, v3 offset0:64 offset1:80
	ds_read2_b32 v[2:3], v7 offset0:128 offset1:144
	s_waitcnt lgkmcnt(0)
	v_fma_f32 v2, v43, v5, v2
	v_fmac_f32_e32 v3, v27, v4
	ds_write2_b32 v7, v2, v3 offset0:128 offset1:144
	ds_read2_b32 v[2:3], v7 offset0:192 offset1:208
	s_waitcnt lgkmcnt(0)
	v_fma_f32 v2, v44, v5, v2
	v_fmac_f32_e32 v3, v28, v4
	ds_write2_b32 v7, v2, v3 offset0:192 offset1:208
	v_add_u32_e32 v7, 0x3400, v6
	ds_read2_b32 v[2:3], v7 offset1:16
	s_waitcnt lgkmcnt(0)
	v_fma_f32 v2, v45, v5, v2
	v_fmac_f32_e32 v3, v29, v4
	ds_write2_b32 v7, v2, v3 offset1:16
	v_add_u32_e32 v7, 0x3800, v6
	ds_read2_b32 v[2:3], v7 offset0:64 offset1:80
	v_add_u32_e32 v6, 0x3c00, v6
	s_waitcnt lgkmcnt(0)
	v_fma_f32 v2, v46, v5, v2
	v_fmac_f32_e32 v3, v30, v4
	ds_write2_b32 v7, v2, v3 offset0:64 offset1:80
	ds_read2_b32 v[2:3], v7 offset0:128 offset1:144
	s_waitcnt lgkmcnt(0)
	v_fma_f32 v2, v47, v5, v2
	v_fmac_f32_e32 v3, v31, v4
	ds_write2_b32 v7, v2, v3 offset0:128 offset1:144
	ds_read2_b32 v[2:3], v7 offset0:192 offset1:208
	s_waitcnt lgkmcnt(0)
	v_fma_f32 v2, v48, v5, v2
	v_fmac_f32_e32 v3, v32, v4
	ds_write2_b32 v7, v2, v3 offset0:192 offset1:208
	ds_read2_b32 v[2:3], v6 offset1:16
	s_waitcnt lgkmcnt(0)
	v_fma_f32 v2, v49, v5, v2
	v_fmac_f32_e32 v3, v33, v4
	ds_write2_b32 v6, v2, v3 offset1:16
	s_waitcnt lgkmcnt(0)
	s_cbranch_scc1 .LBB0_648
; __device__ __forceinline__ float bf_lo(unsigned u) { return __uint_as_float(u << 16); }
; __device__ __forceinline__ float bf_hi(unsigned u) { return __uint_as_float(u & 0xffff0000u); }
; __device__ __forceinline__ bf16x8 pack_p(const float* p) { u32x4 w; w.x = cvt_pk_bf16(p[0], p[1]); w.y = cvt_pk_bf16(p[2], p[3]); w.z = cvt_pk_bf16(p[4], p[5]); w.w = cvt_pk_bf16(p[6], p[7]); return __builtin_bit_cast(bf16x8, w); }
; __device__ __forceinline__ void nsa_tile(const Ctx& C, int b, int g, int t0) {
;     ...
;         bf16x8 qr[4];
;         {
;             const bf16_t* qp = P + tok * PP + PC_Q + head * 64;
; #pragma unroll
;             for (int s = 1; s < 4; ++s) qr[s] = scale_q(*(const u32x4*)(qp + 16 * s + 8 * hi), QS);
;             const u32x4 mv4 = *(const u32x4*)(qp + 8 * hi), pv4 = *(const u32x4*)(qp + 8 * (hi ^ 1));
;             const float* rt = (const float*)(C.ws + WS_ROPE) + tok * 16;
;             const f32x4 ca = *(const f32x4*)rt, cb2 = *(const f32x4*)(rt + 4), sa = *(const f32x4*)(rt + 8), sb = *(const f32x4*)(rt + 12);
;             const float cs[8] = {ca.x, ca.y, ca.z, ca.w, cb2.x, cb2.y, cb2.z, cb2.w}, sn[8] = {sa.x, sa.y, sa.z, sa.w, sb.x, sb.y, sb.z, sb.w};
;             const float mv[8] = {bf_lo(mv4.x), bf_hi(mv4.x), bf_lo(mv4.y), bf_hi(mv4.y), bf_lo(mv4.z), bf_hi(mv4.z), bf_lo(mv4.w), bf_hi(mv4.w)};
;             const float pp[8] = {bf_lo(pv4.x), bf_hi(pv4.x), bf_lo(pv4.y), bf_hi(pv4.y), bf_lo(pv4.z), bf_hi(pv4.z), bf_lo(pv4.w), bf_hi(pv4.w)};
;             const float sg = hi ? 1.f : -1.f; float o[8];
; #pragma unroll
;             for (int e = 0; e < 8; ++e) o[e] = (mv[e] * cs[e] + sg * pp[e] * sn[e]) * QS;
;             qr[0] = pack_p(o);
;         }
;         const bf16x8* kb = (const bf16x8*)(C.ws + WS_KWIN) + (size_t)bg * 512 * 4 * 64 + lane;
;         const bf16x8* vb = (const bf16x8*)(C.ws + WS_VWIN) + (size_t)bg * 1024 * 2 * 64 + lane;
;         float m = -1e30f, l = 0.f; f32x16 O[2];
; #pragma unroll
;         for (int i = 0; i < 16; ++i) { O[0][i] = 0.f; O[1][i] = 0.f; }
;         const int tlo = (t0 - 511 > 0 ? t0 - 511 : 0) >> 5, thi = (t0 + 7) >> 5;
	v_xor_b32_e32 v22, 8, v218
	v_lshlrev_b64 v[2:3], 6, v[0:1]
	v_ashrrev_i32_e32 v23, 31, v22
	v_lshl_add_u64 v[14:15], s[78:79], 0, v[2:3]
	v_lshl_add_u64 v[22:23], v[22:23], 1, v[222:223]
	global_load_dwordx4 v[2:5], v[14:15], off offset:16
	global_load_dwordx4 v[6:9], v[14:15], off offset:48
	global_load_dwordx4 v[10:13], v[14:15], off
	s_nop 0
	global_load_dwordx4 v[14:17], v[14:15], off offset:32
	s_nop 0
	global_load_dwordx4 v[18:21], v[220:221], off offset:3072
	v_cmp_gt_u32_e32 vcc, 32, v224
	global_load_dwordx4 v[22:25], v[22:23], off offset:3072
	global_load_dwordx4 v[114:117], v[220:221], off offset:3168
	global_load_dwordx4 v[118:121], v[220:221], off offset:3136
	global_load_dwordx4 v[122:125], v[220:221], off offset:3104
	s_lshl_b64 s[10:11], s[30:31], 21
	s_add_u32 s12, s29, s10
	s_addc_u32 s13, s37, s11
	s_add_u32 s10, s59, s10
	s_addc_u32 s11, s80, s11
	s_and_b32 s5, s1, 0xffffffe0
	s_or_b32 s1, s1, 31
	s_cmp_gt_i32 s1, s97
	v_lshl_add_u64 v[164:165], s[10:11], 0, v[228:229]
	s_cselect_b64 s[10:11], -1, 0
	s_add_i32 s16, s97, 0xfffffe08
	s_cmp_lt_i32 s5, s16
	v_lshl_add_u64 v[162:163], s[12:13], 0, v[228:229]
	s_cselect_b64 s[12:13], -1, 0
	s_or_b64 s[10:11], s[10:11], s[12:13]
	s_and_b64 s[10:11], s[10:11], exec
	s_mov_b32 s1, s7
	s_cselect_b32 s17, 2, 0
	s_lshl_b64 s[10:11], s[0:1], 12
	s_waitcnt vmcnt(6)
	v_mov_b32_e32 v28, v10
	s_waitcnt vmcnt(5)
	v_mov_b32_e32 v29, v14
	s_waitcnt vmcnt(4)
	v_lshlrev_b32_e32 v26, 16, v18
	v_mov_b32_e32 v14, v11
	s_waitcnt vmcnt(3)
	v_lshlrev_b32_e32 v27, 16, v22
	v_cndmask_b32_e64 v27, v27, -v27, vcc
	v_pk_mul_f32 v[26:27], v[28:29], v[26:27]
	s_nop 0
	v_add_f32_e32 v10, v26, v27
	v_mul_f32_e32 v28, 0x3e38aa3b, v10
	v_and_b32_e32 v10, 0xffff0000, v22
	v_and_b32_e32 v26, 0xffff0000, v18
	v_cndmask_b32_e64 v27, v10, -v10, vcc
	v_pk_mul_f32 v[10:11], v[14:15], v[26:27]
	v_mov_b32_e32 v14, v12
	v_add_f32_e32 v10, v10, v11
	v_mul_f32_e32 v10, 0x3e38aa3b, v10
	v_lshlrev_b32_e32 v11, 16, v23
	v_cvt_pk_bf16_f32 v50, v28, v10
	v_lshlrev_b32_e32 v10, 16, v19
	v_cndmask_b32_e64 v11, v11, -v11, vcc
	v_mov_b32_e32 v15, v16
	v_pk_mul_f32 v[10:11], v[14:15], v[10:11]
	v_mov_b32_e32 v16, v13
	v_add_f32_e32 v10, v10, v11
	v_and_b32_e32 v11, 0xffff0000, v23
	v_mul_f32_e32 v12, 0x3e38aa3b, v10
	v_and_b32_e32 v10, 0xffff0000, v19
	v_cndmask_b32_e64 v11, v11, -v11, vcc
	v_pk_mul_f32 v[10:11], v[16:17], v[10:11]
	v_mov_b32_e32 v13, v6
	v_add_f32_e32 v10, v10, v11
	v_mul_f32_e32 v10, 0x3e38aa3b, v10
	v_lshlrev_b32_e32 v11, 16, v24
	v_cvt_pk_bf16_f32 v51, v12, v10
	v_lshlrev_b32_e32 v10, 16, v20
	v_cndmask_b32_e64 v11, v11, -v11, vcc
	v_mov_b32_e32 v12, v2
	v_pk_mul_f32 v[10:11], v[12:13], v[10:11]
	v_mov_b32_e32 v6, v3
	v_add_f32_e32 v2, v10, v11
	v_mul_f32_e32 v12, 0x3e38aa3b, v2
	v_and_b32_e32 v2, 0xffff0000, v24
	v_and_b32_e32 v10, 0xffff0000, v20
	v_cndmask_b32_e64 v11, v2, -v2, vcc
	v_pk_mul_f32 v[2:3], v[6:7], v[10:11]
	v_mov_b32_e32 v6, v4
	v_add_f32_e32 v2, v2, v3
	v_mul_f32_e32 v2, 0x3e38aa3b, v2
	v_lshlrev_b32_e32 v3, 16, v25
	v_cvt_pk_bf16_f32 v52, v12, v2
	v_lshlrev_b32_e32 v2, 16, v21
	v_cndmask_b32_e64 v3, v3, -v3, vcc
	v_mov_b32_e32 v7, v8
	v_pk_mul_f32 v[2:3], v[6:7], v[2:3]
	v_mov_b32_e32 v8, v5
	v_add_f32_e32 v2, v2, v3
	v_and_b32_e32 v3, 0xffff0000, v25
	v_mul_f32_e32 v4, 0x3e38aa3b, v2
	v_and_b32_e32 v2, 0xffff0000, v21
	v_cndmask_b32_e64 v3, v3, -v3, vcc
	v_pk_mul_f32 v[2:3], v[8:9], v[2:3]
	s_nop 0
	v_add_f32_e32 v2, v2, v3
	v_mul_f32_e32 v2, 0x3e38aa3b, v2
	v_cvt_pk_bf16_f32 v53, v4, v2
	s_waitcnt vmcnt(2)
	v_mov_b32_e32 v2, v114
	v_mov_b32_e32 v3, v115
	v_mov_b32_e32 v4, v116
	v_mov_b32_e32 v5, v117
	v_lshlrev_b32_e32 v6, 16, v2
	v_and_b32_e32 v7, 0xffff0000, v2
	v_lshlrev_b32_e32 v2, 16, v3
	v_and_b32_e32 v3, 0xffff0000, v3
	v_pk_mul_f32 v[2:3], v[2:3], s[38:39] op_sel_hi:[1,0]
	v_pk_mul_f32 v[6:7], v[6:7], s[38:39] op_sel_hi:[1,0]
	v_cvt_pk_bf16_f32 v55, v2, v3
	v_lshlrev_b32_e32 v2, 16, v4
	v_and_b32_e32 v3, 0xffff0000, v4
	v_pk_mul_f32 v[2:3], v[2:3], s[38:39] op_sel_hi:[1,0]
	v_cvt_pk_bf16_f32 v54, v6, v7
	v_cvt_pk_bf16_f32 v56, v2, v3
	v_lshlrev_b32_e32 v2, 16, v5
	v_and_b32_e32 v3, 0xffff0000, v5
	v_pk_mul_f32 v[2:3], v[2:3], s[38:39] op_sel_hi:[1,0]
	s_nop 0
	v_cvt_pk_bf16_f32 v57, v2, v3
	s_waitcnt vmcnt(1)
	v_mov_b32_e32 v2, v118
	v_mov_b32_e32 v3, v119
	v_mov_b32_e32 v4, v120
	v_mov_b32_e32 v5, v121
	v_lshlrev_b32_e32 v6, 16, v2
	v_and_b32_e32 v7, 0xffff0000, v2
	v_lshlrev_b32_e32 v2, 16, v3
	v_and_b32_e32 v3, 0xffff0000, v3
	v_pk_mul_f32 v[2:3], v[2:3], s[38:39] op_sel_hi:[1,0]
	v_pk_mul_f32 v[6:7], v[6:7], s[38:39] op_sel_hi:[1,0]
	v_cvt_pk_bf16_f32 v59, v2, v3
	v_lshlrev_b32_e32 v2, 16, v4
	v_and_b32_e32 v3, 0xffff0000, v4
	v_pk_mul_f32 v[2:3], v[2:3], s[38:39] op_sel_hi:[1,0]
	v_cvt_pk_bf16_f32 v58, v6, v7
	v_cvt_pk_bf16_f32 v60, v2, v3
	v_lshlrev_b32_e32 v2, 16, v5
	v_and_b32_e32 v3, 0xffff0000, v5
	v_pk_mul_f32 v[2:3], v[2:3], s[38:39] op_sel_hi:[1,0]
	s_nop 0
	v_cvt_pk_bf16_f32 v61, v2, v3
	s_waitcnt vmcnt(0)
; #define LAS __attribute__((address_space(3)))
; __device__ __forceinline__ void flash_compute(bool domask, const bf16x8 (&kf)[4], const bf16x8 (&vf)[4], const bf16x8 (&q)[4], int x0, unsigned span, float& m, float& l, f32x16 (&O)[2]) {
;     f32x16 sc;
; #pragma unroll
;     for (int i = 0; i < 16; ++i) sc[i] = 0.f;
;     __builtin_amdgcn_s_setprio(1);
; #pragma unroll
;     for (int s = 0; s < 4; ++s) sc = mfma32(kf[s], q[s], sc);
;     __builtin_amdgcn_s_setprio(0);
;     if (domask) {
; #pragma unroll
;         for (int i = 0; i < 16; ++i) sc[i] = ((unsigned)(x0 + i + (i >= 8 ? 8 : 0)) <= span) ? sc[i] : -1e30f;
;     }
;     const float a0 = fmaxf(fmaxf(sc[0], sc[1]), sc[2]), a1 = fmaxf(fmaxf(sc[3], sc[4]), sc[5]), a2 = fmaxf(fmaxf(sc[6], sc[7]), sc[8]), a3 = fmaxf(fmaxf(sc[9], sc[10]), sc[11]), a4 = fmaxf(fmaxf(sc[12], sc[13]), sc[14]);
;     float mx = fmaxf(fmaxf(fmaxf(a0, a1), fmaxf(a2, a3)), fmaxf(a4, sc[15]));
;     mx = xhalf_max(mx);
;     const bool upd = mx > m + SM_THR;
;     if (__ballot(upd) != 0ull) {
; template <int MODE> __device__ __forceinline__ void flash_desc(int s, const LAS unsigned* list, int base, int t, int t0, int qi, int hi, int& tile, int& x0, unsigned& span, int& vm) {
;     ...
;         tile = base + s; x0 = 8 * hi - (t - 511 - 32 * tile); span = 511u;
;         vm = (32 * tile + 31 <= t0 && 32 * tile >= t0 + 7 - 511) ? 0 : 2;
;     }
; }
; template <int MODE> __device__ __forceinline__ void flash_run(const bf16x8* kb, const bf16x8* vb, const bf16x8 (&q)[4], int nsteps, const LAS unsigned* list, int base, int t, int t0, int qi, int hi, float& m, float& l, f32x16 (&O)[2]) {
;     if (nsteps <= 0) return;
;     bf16x8 kA[4], vA[4], kB[4], vB[4], kC[4], vC[4]; int x0A, x0B, x0C, vmA, vmB, vmC; unsigned spA, spB, spC;
;     ...
;     FR_LOAD(0, kA, vA, x0A, spA, vmA); FR_LOAD(1, kB, vB, x0B, spB, vmB);
; #pragma unroll 1
;     for (int s = 0; s < nsteps; s += 3) {
;         FR_LOAD(s + 2, kC, vC, x0C, spC, vmC); flash_compute(vmA != 0, kA, vA, q, x0A, spA, m, l, O); if (s + 1 >= nsteps) break;
;         FR_LOAD(s + 3, kA, vA, x0A, spA, vmA); flash_compute(vmB != 0, kB, vB, q, x0B, spB, m, l, O); if (s + 2 >= nsteps) break;
;         FR_LOAD(s + 4, kB, vB, x0B, spB, vmB); flash_compute(vmC != 0, kC, vC, q, x0C, spC, m, l, O);
;     }
	v_mov_b32_e32 v2, v122
	v_mov_b32_e32 v3, v123
	v_mov_b32_e32 v4, v124
	v_mov_b32_e32 v5, v125
	v_lshlrev_b32_e32 v6, 16, v2
	v_and_b32_e32 v7, 0xffff0000, v2
	v_lshlrev_b32_e32 v2, 16, v3
	v_and_b32_e32 v3, 0xffff0000, v3
	v_pk_mul_f32 v[2:3], v[2:3], s[38:39] op_sel_hi:[1,0]
	v_pk_mul_f32 v[6:7], v[6:7], s[38:39] op_sel_hi:[1,0]
	v_cvt_pk_bf16_f32 v63, v2, v3
	v_lshlrev_b32_e32 v2, 16, v4
	v_and_b32_e32 v3, 0xffff0000, v4
	v_pk_mul_f32 v[2:3], v[2:3], s[38:39] op_sel_hi:[1,0]
	v_cvt_pk_bf16_f32 v62, v6, v7
	v_cvt_pk_bf16_f32 v64, v2, v3
	v_lshlrev_b32_e32 v2, 16, v5
	v_and_b32_e32 v3, 0xffff0000, v5
	v_pk_mul_f32 v[2:3], v[2:3], s[38:39] op_sel_hi:[1,0]
	v_lshl_add_u64 v[4:5], v[164:165], 0, s[10:11]
	v_cvt_pk_bf16_f32 v65, v2, v3
	v_lshl_add_u64 v[2:3], v[162:163], 0, s[10:11]
	v_add_u32_e32 v201, 0x1ff, v218
	v_sub_u32_e32 v201, v201, v242
	s_add_i32 s13, s97, 0xfffffe08
	v_mov_b32_e32 v2, v1
	v_mov_b32_e32 v3, v1
	v_mov_b32_e32 v4, v1
	v_mov_b32_e32 v5, v1
	v_mov_b32_e32 v6, v1
	v_mov_b32_e32 v7, v1
	v_mov_b32_e32 v8, v1
	v_mov_b32_e32 v9, v1
	v_mov_b32_e32 v10, v1
	v_mov_b32_e32 v11, v1
	v_mov_b32_e32 v12, v1
	v_mov_b32_e32 v13, v1
	v_mov_b32_e32 v14, v1
	v_mov_b32_e32 v15, v1
	v_mov_b32_e32 v16, v1
	v_mov_b32_e32 v17, v1
	v_mov_b32_e32 v18, v1
	v_mov_b32_e32 v19, v1
	v_mov_b32_e32 v20, v1
	v_mov_b32_e32 v21, v1
	v_mov_b32_e32 v22, v1
	v_mov_b32_e32 v23, v1
	v_mov_b32_e32 v24, v1
	v_mov_b32_e32 v25, v1
	v_mov_b32_e32 v26, v1
	v_mov_b32_e32 v27, v1
	v_mov_b32_e32 v28, v1
	v_mov_b32_e32 v29, v1
	v_mov_b32_e32 v30, v1
	v_mov_b32_e32 v31, v1
	v_mov_b32_e32 v32, v1
	v_mov_b32_e32 v33, v1
	v_mov_b32_e32 v170, 0
	v_mov_b32_e32 v171, 0
	v_mov_b32_e32 v172, 0
	v_mov_b32_e32 v173, 0
	v_mov_b32_e32 v174, 0
	v_mov_b32_e32 v175, 0
	v_mov_b32_e32 v176, 0
	v_mov_b32_e32 v177, 0
	v_mov_b32_e32 v178, 0
	v_mov_b32_e32 v179, 0
	v_mov_b32_e32 v180, 0
	v_mov_b32_e32 v181, 0
	v_mov_b32_e32 v182, 0
	v_mov_b32_e32 v183, 0
	v_mov_b32_e32 v184, 0
	v_mov_b32_e32 v185, 0
	v_mov_b32_e32 v166, 0
	v_mov_b32_e32 v168, v249
	v_mov_b32_e32 v200, v249
	v_mov_b32_e32 v202, 0x41000000
	s_mov_b32 s3, 0
	s_add_i32 s6, s3, 0
	s_min_i32 s6, s6, s2
	s_add_i32 s6, s6, s0
	s_lshl_b32 s6, s6, 12
	v_lshl_add_u64 v[194:195], v[162:163], 0, s[6:7]
	v_lshl_add_u64 v[196:197], v[164:165], 0, s[6:7]
	global_load_dwordx4 v[66:69], v[194:195], off
	global_load_dwordx4 v[70:73], v[194:195], off offset:1024
	global_load_dwordx4 v[74:77], v[194:195], off offset:2048
	global_load_dwordx4 v[78:81], v[194:195], off offset:3072
	global_load_dwordx4 v[82:85], v[196:197], off
	global_load_dwordx4 v[86:89], v[196:197], off offset:1024
	global_load_dwordx4 v[90:93], v[196:197], off offset:2048
	global_load_dwordx4 v[94:97], v[196:197], off offset:3072
	s_add_i32 s6, s3, 1
	s_min_i32 s6, s6, s2
	s_add_i32 s6, s6, s0
	s_lshl_b32 s6, s6, 12
	v_lshl_add_u64 v[194:195], v[162:163], 0, s[6:7]
	v_lshl_add_u64 v[196:197], v[164:165], 0, s[6:7]
	global_load_dwordx4 v[98:101], v[194:195], off
	global_load_dwordx4 v[102:105], v[194:195], off offset:1024
	global_load_dwordx4 v[106:109], v[194:195], off offset:2048
	global_load_dwordx4 v[110:113], v[194:195], off offset:3072
	global_load_dwordx4 v[114:117], v[196:197], off
	global_load_dwordx4 v[118:121], v[196:197], off offset:1024
	global_load_dwordx4 v[122:125], v[196:197], off offset:2048
	global_load_dwordx4 v[126:129], v[196:197], off offset:3072
.Lwin_step_A:
	s_add_i32 s6, s3, 2
	s_min_i32 s6, s6, s2
	s_add_i32 s6, s6, s0
	s_lshl_b32 s6, s6, 12
	v_lshl_add_u64 v[194:195], v[162:163], 0, s[6:7]
	v_lshl_add_u64 v[196:197], v[164:165], 0, s[6:7]
	global_load_dwordx4 v[130:133], v[194:195], off
	global_load_dwordx4 v[134:137], v[194:195], off offset:1024
	global_load_dwordx4 v[138:141], v[194:195], off offset:2048
	global_load_dwordx4 v[142:145], v[194:195], off offset:3072
	global_load_dwordx4 v[146:149], v[196:197], off
	global_load_dwordx4 v[150:153], v[196:197], off offset:1024
	global_load_dwordx4 v[154:157], v[196:197], off offset:2048
	global_load_dwordx4 v[158:161], v[196:197], off offset:3072
	s_add_i32 s1, s0, s3
	s_lshl_b32 s10, s1, 5
	s_or_b32 s11, s10, 31
	s_cmp_gt_u32 s11, s97
	s_cselect_b32 s12, 1, 0
	s_cmp_lt_i32 s10, s13
	s_cselect_b32 s12, 1, s12
	s_waitcnt vmcnt(20)
	s_cmp_eq_u32 s12, 0
	s_cbranch_scc0 .Lwin_edge_A
	v_mfma_f32_32x32x16_bf16 v[34:49], v[66:69], v[50:53], v[170:185]
.Lwin_qk_A:
	v_mfma_f32_32x32x16_bf16 v[34:49], v[70:73], v[62:65], v[34:49]
	v_mfma_f32_32x32x16_bf16 v[34:49], v[74:77], v[58:61], v[34:49]
	v_mfma_f32_32x32x16_bf16 v[34:49], v[78:81], v[54:57], v[34:49]
	s_nop 11
	v_max3_f32 v198, v34, v35, v36
	v_max3_f32 v199, v37, v38, v39
	v_max3_f32 v198, v198, v40, v41
	v_max3_f32 v199, v199, v42, v43
	v_max3_f32 v198, v198, v44, v45
	v_max3_f32 v199, v199, v46, v47
	v_max3_f32 v198, v198, v48, v49
	v_max_f32_e32 v198, v198, v199
	v_mov_b32_e32 v199, v198
	s_nop 1
	v_permlane32_swap_b32_e32 v198, v199
	v_max_f32_e32 v198, v198, v199
	v_cmp_gt_f32_e32 vcc, v198, v200
	s_cbranch_vccnz .Lwin_upd_A
; __device__ __forceinline__ float ex2(float x) { return __builtin_amdgcn_exp2f(x); }
; __device__ __forceinline__ float xhalf_max(float v) { const auto r = __builtin_amdgcn_permlane32_swap(__float_as_uint(v), __float_as_uint(v), false, false); return fmaxf(__uint_as_float(r[0]), __uint_as_float(r[1])); }
; __device__ __forceinline__ f32x16 mfma32(bf16x8 a, bf16x8 b, f32x16 c) { return __builtin_amdgcn_mfma_f32_32x32x16_bf16(a, b, c, 0, 0, 0); }
; __device__ __forceinline__ void flash_compute(bool domask, const bf16x8 (&kf)[4], const bf16x8 (&vf)[4], const bf16x8 (&q)[4], int x0, unsigned span, float& m, float& l, f32x16 (&O)[2]) {
;     ...
;     const float a0 = fmaxf(fmaxf(sc[0], sc[1]), sc[2]), a1 = fmaxf(fmaxf(sc[3], sc[4]), sc[5]), a2 = fmaxf(fmaxf(sc[6], sc[7]), sc[8]), a3 = fmaxf(fmaxf(sc[9], sc[10]), sc[11]), a4 = fmaxf(fmaxf(sc[12], sc[13]), sc[14]);
;     float mx = fmaxf(fmaxf(fmaxf(a0, a1), fmaxf(a2, a3)), fmaxf(a4, sc[15]));
;     mx = xhalf_max(mx);
;     const bool upd = mx > m + SM_THR;
;     if (__ballot(upd) != 0ull) {
;         const float mn = upd ? mx : m, alpha = ex2(m - mn); l *= alpha; O[0] = O[0] * alpha; O[1] = O[1] * alpha; m = mn;
;     }
;     const float msub = (m < -1e29f) ? 0.f : m;
;     const f32x16 d = sc - msub;
;     float p[16], ps = 0.f;
; #pragma unroll
;     for (int i = 0; i < 16; ++i) { p[i] = ex2(d[i]); ps += p[i]; }
;     l += ps;
;     const bf16x8 pb0 = pack_p(p), pb1 = pack_p(p + 8);
;     __builtin_amdgcn_s_setprio(1);
;     O[0] = mfma32(vf[0], pb0, O[0]); O[1] = mfma32(vf[1], pb0, O[1]);
;     O[0] = mfma32(vf[2], pb1, O[0]); O[1] = mfma32(vf[3], pb1, O[1]);
;     __builtin_amdgcn_s_setprio(0);
; template <int MODE> __device__ __forceinline__ void flash_run(const bf16x8* kb, const bf16x8* vb, const bf16x8 (&q)[4], int nsteps, const LAS unsigned* list, int base, int t, int t0, int qi, int hi, float& m, float& l, f32x16 (&O)[2]) {
;     ...
;     for (int s = 0; s < nsteps; s += 3) {
;         FR_LOAD(s + 2, kC, vC, x0C, spC, vmC); flash_compute(vmA != 0, kA, vA, q, x0A, spA, m, l, O); if (s + 1 >= nsteps) break;
;         FR_LOAD(s + 3, kA, vA, x0A, spA, vmA); flash_compute(vmB != 0, kB, vB, q, x0B, spB, m, l, O); if (s + 2 >= nsteps) break;
;         FR_LOAD(s + 4, kB, vB, x0B, spB, vmB); flash_compute(vmC != 0, kC, vC, q, x0C, spC, m, l, O);
.Lwin_noupd_A:
	v_exp_f32_e32 v34, v34
	v_exp_f32_e32 v35, v35
	v_exp_f32_e32 v36, v36
	v_exp_f32_e32 v37, v37
	v_exp_f32_e32 v38, v38
	v_exp_f32_e32 v39, v39
	v_exp_f32_e32 v40, v40
	v_exp_f32_e32 v41, v41
	v_exp_f32_e32 v42, v42
	v_exp_f32_e32 v43, v43
	v_exp_f32_e32 v44, v44
	v_exp_f32_e32 v45, v45
	v_exp_f32_e32 v46, v46
	v_exp_f32_e32 v47, v47
	v_exp_f32_e32 v48, v48
	v_exp_f32_e32 v49, v49
	v_cvt_pk_bf16_f32 v186, v34, v35
	v_cvt_pk_bf16_f32 v187, v36, v37
	v_cvt_pk_bf16_f32 v188, v38, v39
	v_cvt_pk_bf16_f32 v189, v40, v41
	v_cvt_pk_bf16_f32 v190, v42, v43
	v_cvt_pk_bf16_f32 v191, v44, v45
	v_cvt_pk_bf16_f32 v192, v46, v47
	v_cvt_pk_bf16_f32 v193, v48, v49
	v_add_f32_e32 v198, v34, v35
	v_add_f32_e32 v198, v198, v36
	v_add_f32_e32 v198, v198, v37
	v_add_f32_e32 v198, v198, v38
	v_add_f32_e32 v198, v198, v39
	v_add_f32_e32 v198, v198, v40
	v_add_f32_e32 v198, v198, v41
	v_add_f32_e32 v198, v198, v42
	v_add_f32_e32 v198, v198, v43
	v_add_f32_e32 v198, v198, v44
	v_add_f32_e32 v198, v198, v45
	v_add_f32_e32 v198, v198, v46
	v_add_f32_e32 v198, v198, v47
	v_add_f32_e32 v198, v198, v48
	v_add_f32_e32 v198, v198, v49
	v_add_f32_e32 v166, v166, v198
	s_waitcnt vmcnt(16)
	v_mfma_f32_32x32x16_bf16 v[18:33], v[82:85], v[186:189], v[18:33]
	v_mfma_f32_32x32x16_bf16 v[2:17], v[86:89], v[186:189], v[2:17]
	v_mfma_f32_32x32x16_bf16 v[18:33], v[90:93], v[190:193], v[18:33]
	v_mfma_f32_32x32x16_bf16 v[2:17], v[94:97], v[190:193], v[2:17]
	s_add_i32 s3, s3, 1
	s_cmp_gt_i32 s3, s2
	s_cbranch_scc1 .Lwin_done
.Lwin_step_B:
	s_add_i32 s6, s3, 2
	s_min_i32 s6, s6, s2
	s_add_i32 s6, s6, s0
	s_lshl_b32 s6, s6, 12
	v_lshl_add_u64 v[194:195], v[162:163], 0, s[6:7]
	v_lshl_add_u64 v[196:197], v[164:165], 0, s[6:7]
	global_load_dwordx4 v[66:69], v[194:195], off
	global_load_dwordx4 v[70:73], v[194:195], off offset:1024
	global_load_dwordx4 v[74:77], v[194:195], off offset:2048
	global_load_dwordx4 v[78:81], v[194:195], off offset:3072
	global_load_dwordx4 v[82:85], v[196:197], off
	global_load_dwordx4 v[86:89], v[196:197], off offset:1024
	global_load_dwordx4 v[90:93], v[196:197], off offset:2048
	global_load_dwordx4 v[94:97], v[196:197], off offset:3072
	s_add_i32 s1, s0, s3
	s_lshl_b32 s10, s1, 5
	s_or_b32 s11, s10, 31
	s_cmp_gt_u32 s11, s97
	s_cselect_b32 s12, 1, 0
	s_cmp_lt_i32 s10, s13
	s_cselect_b32 s12, 1, s12
	s_waitcnt vmcnt(20)
	s_cmp_eq_u32 s12, 0
	s_cbranch_scc0 .Lwin_edge_B
	v_mfma_f32_32x32x16_bf16 v[34:49], v[98:101], v[50:53], v[170:185]
.Lwin_qk_B:
	v_mfma_f32_32x32x16_bf16 v[34:49], v[102:105], v[62:65], v[34:49]
	v_mfma_f32_32x32x16_bf16 v[34:49], v[106:109], v[58:61], v[34:49]
	v_mfma_f32_32x32x16_bf16 v[34:49], v[110:113], v[54:57], v[34:49]
	s_nop 11
	v_max3_f32 v198, v34, v35, v36
	v_max3_f32 v199, v37, v38, v39
	v_max3_f32 v198, v198, v40, v41
	v_max3_f32 v199, v199, v42, v43
	v_max3_f32 v198, v198, v44, v45
	v_max3_f32 v199, v199, v46, v47
	v_max3_f32 v198, v198, v48, v49
	v_max_f32_e32 v198, v198, v199
	v_mov_b32_e32 v199, v198
	s_nop 1
	v_permlane32_swap_b32_e32 v198, v199
	v_max_f32_e32 v198, v198, v199
	v_cmp_gt_f32_e32 vcc, v198, v200
	s_cbranch_vccnz .Lwin_upd_B
.Lwin_noupd_B:
	v_exp_f32_e32 v34, v34
	v_exp_f32_e32 v35, v35
	v_exp_f32_e32 v36, v36
	v_exp_f32_e32 v37, v37
	v_exp_f32_e32 v38, v38
	v_exp_f32_e32 v39, v39
	v_exp_f32_e32 v40, v40
	v_exp_f32_e32 v41, v41
	v_exp_f32_e32 v42, v42
	v_exp_f32_e32 v43, v43
	v_exp_f32_e32 v44, v44
	v_exp_f32_e32 v45, v45
	v_exp_f32_e32 v46, v46
	v_exp_f32_e32 v47, v47
	v_exp_f32_e32 v48, v48
	v_exp_f32_e32 v49, v49
	v_cvt_pk_bf16_f32 v186, v34, v35
	v_cvt_pk_bf16_f32 v187, v36, v37
	v_cvt_pk_bf16_f32 v188, v38, v39
	v_cvt_pk_bf16_f32 v189, v40, v41
	v_cvt_pk_bf16_f32 v190, v42, v43
	v_cvt_pk_bf16_f32 v191, v44, v45
	v_cvt_pk_bf16_f32 v192, v46, v47
	v_cvt_pk_bf16_f32 v193, v48, v49
	v_add_f32_e32 v198, v34, v35
	v_add_f32_e32 v198, v198, v36
	v_add_f32_e32 v198, v198, v37
	v_add_f32_e32 v198, v198, v38
	v_add_f32_e32 v198, v198, v39
	v_add_f32_e32 v198, v198, v40
	v_add_f32_e32 v198, v198, v41
	v_add_f32_e32 v198, v198, v42
	v_add_f32_e32 v198, v198, v43
	v_add_f32_e32 v198, v198, v44
	v_add_f32_e32 v198, v198, v45
	v_add_f32_e32 v198, v198, v46
	v_add_f32_e32 v198, v198, v47
	v_add_f32_e32 v198, v198, v48
	v_add_f32_e32 v198, v198, v49
	v_add_f32_e32 v166, v166, v198
	s_waitcnt vmcnt(16)
	v_mfma_f32_32x32x16_bf16 v[18:33], v[114:117], v[186:189], v[18:33]
	v_mfma_f32_32x32x16_bf16 v[2:17], v[118:121], v[186:189], v[2:17]
	v_mfma_f32_32x32x16_bf16 v[18:33], v[122:125], v[190:193], v[18:33]
	v_mfma_f32_32x32x16_bf16 v[2:17], v[126:129], v[190:193], v[2:17]
	s_add_i32 s3, s3, 1
	s_cmp_gt_i32 s3, s2
	s_cbranch_scc1 .Lwin_done
.Lwin_step_C:
	s_add_i32 s6, s3, 2
	s_min_i32 s6, s6, s2
	s_add_i32 s6, s6, s0
	s_lshl_b32 s6, s6, 12
	v_lshl_add_u64 v[194:195], v[162:163], 0, s[6:7]
	v_lshl_add_u64 v[196:197], v[164:165], 0, s[6:7]
	global_load_dwordx4 v[98:101], v[194:195], off
	global_load_dwordx4 v[102:105], v[194:195], off offset:1024
	global_load_dwordx4 v[106:109], v[194:195], off offset:2048
	global_load_dwordx4 v[110:113], v[194:195], off offset:3072
	global_load_dwordx4 v[114:117], v[196:197], off
	global_load_dwordx4 v[118:121], v[196:197], off offset:1024
	global_load_dwordx4 v[122:125], v[196:197], off offset:2048
	global_load_dwordx4 v[126:129], v[196:197], off offset:3072
	s_add_i32 s1, s0, s3
	s_lshl_b32 s10, s1, 5
	s_or_b32 s11, s10, 31
	s_cmp_gt_u32 s11, s97
	s_cselect_b32 s12, 1, 0
	s_cmp_lt_i32 s10, s13
	s_cselect_b32 s12, 1, s12
	s_waitcnt vmcnt(20)
	s_cmp_eq_u32 s12, 0
	s_cbranch_scc0 .Lwin_edge_C
	v_mfma_f32_32x32x16_bf16 v[34:49], v[130:133], v[50:53], v[170:185]
; __device__ __forceinline__ float ex2(float x) { return __builtin_amdgcn_exp2f(x); }
; __device__ __forceinline__ void flash_compute(bool domask, const bf16x8 (&kf)[4], const bf16x8 (&vf)[4], const bf16x8 (&q)[4], int x0, unsigned span, float& m, float& l, f32x16 (&O)[2]) {
;     f32x16 sc;
; #pragma unroll
;     for (int i = 0; i < 16; ++i) sc[i] = 0.f;
;     __builtin_amdgcn_s_setprio(1);
; #pragma unroll
;     for (int s = 0; s < 4; ++s) sc = mfma32(kf[s], q[s], sc);
;     __builtin_amdgcn_s_setprio(0);
;     if (domask) {
; #pragma unroll
;         for (int i = 0; i < 16; ++i) sc[i] = ((unsigned)(x0 + i + (i >= 8 ? 8 : 0)) <= span) ? sc[i] : -1e30f;
;     }
;     const float a0 = fmaxf(fmaxf(sc[0], sc[1]), sc[2]), a1 = fmaxf(fmaxf(sc[3], sc[4]), sc[5]), a2 = fmaxf(fmaxf(sc[6], sc[7]), sc[8]), a3 = fmaxf(fmaxf(sc[9], sc[10]), sc[11]), a4 = fmaxf(fmaxf(sc[12], sc[13]), sc[14]);
;     float mx = fmaxf(fmaxf(fmaxf(a0, a1), fmaxf(a2, a3)), fmaxf(a4, sc[15]));
;     mx = xhalf_max(mx);
;     const bool upd = mx > m + SM_THR;
;     if (__ballot(upd) != 0ull) {
;         const float mn = upd ? mx : m, alpha = ex2(m - mn); l *= alpha; O[0] = O[0] * alpha; O[1] = O[1] * alpha; m = mn;
;     }
;     const float msub = (m < -1e29f) ? 0.f : m;
;     const f32x16 d = sc - msub;
;     float p[16], ps = 0.f;
; #pragma unroll
;     for (int i = 0; i < 16; ++i) { p[i] = ex2(d[i]); ps += p[i]; }
;     l += ps;
;     const bf16x8 pb0 = pack_p(p), pb1 = pack_p(p + 8);
;     __builtin_amdgcn_s_setprio(1);
;     O[0] = mfma32(vf[0], pb0, O[0]); O[1] = mfma32(vf[1], pb0, O[1]);
;     O[0] = mfma32(vf[2], pb1, O[0]); O[1] = mfma32(vf[3], pb1, O[1]);
;     __builtin_amdgcn_s_setprio(0);
; template <int MODE> __device__ __forceinline__ void flash_run(const bf16x8* kb, const bf16x8* vb, const bf16x8 (&q)[4], int nsteps, const LAS unsigned* list, int base, int t, int t0, int qi, int hi, float& m, float& l, f32x16 (&O)[2]) {
;     ...
;         FR_LOAD(s + 2, kC, vC, x0C, spC, vmC); flash_compute(vmA != 0, kA, vA, q, x0A, spA, m, l, O); if (s + 1 >= nsteps) break;
;         FR_LOAD(s + 3, kA, vA, x0A, spA, vmA); flash_compute(vmB != 0, kB, vB, q, x0B, spB, m, l, O); if (s + 2 >= nsteps) break;
;         FR_LOAD(s + 4, kB, vB, x0B, spB, vmB); flash_compute(vmC != 0, kC, vC, q, x0C, spC, m, l, O);
.Lwin_qk_C:
	v_mfma_f32_32x32x16_bf16 v[34:49], v[134:137], v[62:65], v[34:49]
	v_mfma_f32_32x32x16_bf16 v[34:49], v[138:141], v[58:61], v[34:49]
	v_mfma_f32_32x32x16_bf16 v[34:49], v[142:145], v[54:57], v[34:49]
	s_nop 11
	v_max3_f32 v198, v34, v35, v36
	v_max3_f32 v199, v37, v38, v39
	v_max3_f32 v198, v198, v40, v41
	v_max3_f32 v199, v199, v42, v43
	v_max3_f32 v198, v198, v44, v45
	v_max3_f32 v199, v199, v46, v47
	v_max3_f32 v198, v198, v48, v49
	v_max_f32_e32 v198, v198, v199
	v_mov_b32_e32 v199, v198
	s_nop 1
	v_permlane32_swap_b32_e32 v198, v199
	v_max_f32_e32 v198, v198, v199
	v_cmp_gt_f32_e32 vcc, v198, v200
	s_cbranch_vccnz .Lwin_upd_C
.Lwin_noupd_C:
	v_exp_f32_e32 v34, v34
	v_exp_f32_e32 v35, v35
	v_exp_f32_e32 v36, v36
	v_exp_f32_e32 v37, v37
	v_exp_f32_e32 v38, v38
	v_exp_f32_e32 v39, v39
	v_exp_f32_e32 v40, v40
	v_exp_f32_e32 v41, v41
	v_exp_f32_e32 v42, v42
	v_exp_f32_e32 v43, v43
	v_exp_f32_e32 v44, v44
	v_exp_f32_e32 v45, v45
	v_exp_f32_e32 v46, v46
	v_exp_f32_e32 v47, v47
	v_exp_f32_e32 v48, v48
	v_exp_f32_e32 v49, v49
	v_cvt_pk_bf16_f32 v186, v34, v35
	v_cvt_pk_bf16_f32 v187, v36, v37
	v_cvt_pk_bf16_f32 v188, v38, v39
	v_cvt_pk_bf16_f32 v189, v40, v41
	v_cvt_pk_bf16_f32 v190, v42, v43
	v_cvt_pk_bf16_f32 v191, v44, v45
	v_cvt_pk_bf16_f32 v192, v46, v47
	v_cvt_pk_bf16_f32 v193, v48, v49
	v_add_f32_e32 v198, v34, v35
	v_add_f32_e32 v198, v198, v36
	v_add_f32_e32 v198, v198, v37
	v_add_f32_e32 v198, v198, v38
	v_add_f32_e32 v198, v198, v39
	v_add_f32_e32 v198, v198, v40
	v_add_f32_e32 v198, v198, v41
	v_add_f32_e32 v198, v198, v42
	v_add_f32_e32 v198, v198, v43
	v_add_f32_e32 v198, v198, v44
	v_add_f32_e32 v198, v198, v45
	v_add_f32_e32 v198, v198, v46
	v_add_f32_e32 v198, v198, v47
	v_add_f32_e32 v198, v198, v48
	v_add_f32_e32 v198, v198, v49
	v_add_f32_e32 v166, v166, v198
	s_waitcnt vmcnt(16)
	v_mfma_f32_32x32x16_bf16 v[18:33], v[146:149], v[186:189], v[18:33]
	v_mfma_f32_32x32x16_bf16 v[2:17], v[150:153], v[186:189], v[2:17]
	v_mfma_f32_32x32x16_bf16 v[18:33], v[154:157], v[190:193], v[18:33]
	v_mfma_f32_32x32x16_bf16 v[2:17], v[158:161], v[190:193], v[2:17]
	s_add_i32 s3, s3, 1
	s_cmp_le_i32 s3, s2
	s_cbranch_scc1 .Lwin_step_A
.Lwin_done:
	s_waitcnt vmcnt(0)
	v_mov_b64_e32 v[214:215], v[216:217]
	v_mov_b64_e32 v[236:237], 0x1ff
	s_branch .LBB0_649
.Lwin_edge_A:
	v_add_u32_e32 v199, s10, v201
	v_cmp_gt_u32_e32 vcc, 0x200, v199
	s_nop 1
	v_cndmask_b32_e32 v34, v249, v170, vcc
	v_add_u32_e32 v198, 1, v199
	v_cmp_gt_u32_e32 vcc, 0x200, v198
	s_nop 1
	v_cndmask_b32_e32 v35, v249, v170, vcc
	v_add_u32_e32 v198, 2, v199
	v_cmp_gt_u32_e32 vcc, 0x200, v198
	s_nop 1
	v_cndmask_b32_e32 v36, v249, v170, vcc
	v_add_u32_e32 v198, 3, v199
	v_cmp_gt_u32_e32 vcc, 0x200, v198
	s_nop 1
	v_cndmask_b32_e32 v37, v249, v170, vcc
	v_add_u32_e32 v198, 4, v199
	v_cmp_gt_u32_e32 vcc, 0x200, v198
	s_nop 1
	v_cndmask_b32_e32 v38, v249, v170, vcc
	v_add_u32_e32 v198, 5, v199
	v_cmp_gt_u32_e32 vcc, 0x200, v198
	s_nop 1
	v_cndmask_b32_e32 v39, v249, v170, vcc
	v_add_u32_e32 v198, 6, v199
	v_cmp_gt_u32_e32 vcc, 0x200, v198
	s_nop 1
	v_cndmask_b32_e32 v40, v249, v170, vcc
	v_add_u32_e32 v198, 7, v199
	v_cmp_gt_u32_e32 vcc, 0x200, v198
	s_nop 1
	v_cndmask_b32_e32 v41, v249, v170, vcc
	v_add_u32_e32 v198, 16, v199
	v_cmp_gt_u32_e32 vcc, 0x200, v198
	s_nop 1
	v_cndmask_b32_e32 v42, v249, v170, vcc
	v_add_u32_e32 v198, 17, v199
	v_cmp_gt_u32_e32 vcc, 0x200, v198
	s_nop 1
	v_cndmask_b32_e32 v43, v249, v170, vcc
	v_add_u32_e32 v198, 18, v199
	v_cmp_gt_u32_e32 vcc, 0x200, v198
	s_nop 1
	v_cndmask_b32_e32 v44, v249, v170, vcc
	v_add_u32_e32 v198, 19, v199
	v_cmp_gt_u32_e32 vcc, 0x200, v198
	s_nop 1
	v_cndmask_b32_e32 v45, v249, v170, vcc
	v_add_u32_e32 v198, 20, v199
	v_cmp_gt_u32_e32 vcc, 0x200, v198
	s_nop 1
	v_cndmask_b32_e32 v46, v249, v170, vcc
	v_add_u32_e32 v198, 21, v199
	v_cmp_gt_u32_e32 vcc, 0x200, v198
	s_nop 1
	v_cndmask_b32_e32 v47, v249, v170, vcc
	v_add_u32_e32 v198, 22, v199
	v_cmp_gt_u32_e32 vcc, 0x200, v198
	s_nop 1
	v_cndmask_b32_e32 v48, v249, v170, vcc
	v_add_u32_e32 v198, 23, v199
	v_cmp_gt_u32_e32 vcc, 0x200, v198
	s_nop 1
	v_cndmask_b32_e32 v49, v249, v170, vcc
	s_nop 1
	v_mfma_f32_32x32x16_bf16 v[34:49], v[66:69], v[50:53], v[34:49]
	s_branch .Lwin_qk_A
; __device__ __forceinline__ float ex2(float x) { return __builtin_amdgcn_exp2f(x); }
; __device__ __forceinline__ float xhalf_max(float v) { const auto r = __builtin_amdgcn_permlane32_swap(__float_as_uint(v), __float_as_uint(v), false, false); return fmaxf(__uint_as_float(r[0]), __uint_as_float(r[1])); }
; __device__ __forceinline__ f32x16 mfma32(bf16x8 a, bf16x8 b, f32x16 c) { return __builtin_amdgcn_mfma_f32_32x32x16_bf16(a, b, c, 0, 0, 0); }
; __device__ __forceinline__ void flash_compute(bool domask, const bf16x8 (&kf)[4], const bf16x8 (&vf)[4], const bf16x8 (&q)[4], int x0, unsigned span, float& m, float& l, f32x16 (&O)[2]) {
;     ...
;     for (int s = 0; s < 4; ++s) sc = mfma32(kf[s], q[s], sc);
;     __builtin_amdgcn_s_setprio(0);
;     if (domask) {
; #pragma unroll
;         for (int i = 0; i < 16; ++i) sc[i] = ((unsigned)(x0 + i + (i >= 8 ? 8 : 0)) <= span) ? sc[i] : -1e30f;
;     }
;     const float a0 = fmaxf(fmaxf(sc[0], sc[1]), sc[2]), a1 = fmaxf(fmaxf(sc[3], sc[4]), sc[5]), a2 = fmaxf(fmaxf(sc[6], sc[7]), sc[8]), a3 = fmaxf(fmaxf(sc[9], sc[10]), sc[11]), a4 = fmaxf(fmaxf(sc[12], sc[13]), sc[14]);
;     float mx = fmaxf(fmaxf(fmaxf(a0, a1), fmaxf(a2, a3)), fmaxf(a4, sc[15]));
;     mx = xhalf_max(mx);
;     const bool upd = mx > m + SM_THR;
;     if (__ballot(upd) != 0ull) {
;         const float mn = upd ? mx : m, alpha = ex2(m - mn); l *= alpha; O[0] = O[0] * alpha; O[1] = O[1] * alpha; m = mn;
;     }
;     const float msub = (m < -1e29f) ? 0.f : m;
;     const f32x16 d = sc - msub;
.Lwin_upd_A:
	s_nop 1
	v_cndmask_b32_e32 v199, 0, v198, vcc
	v_sub_f32_e32 v197, v198, v170
	v_cndmask_b32_e32 v197, v168, v197, vcc
	v_sub_f32_e32 v196, v168, v197
	v_exp_f32_e32 v196, v196
	v_mov_b32_e32 v168, v197
	v_cndmask_b32_e64 v170, v170, -v197, vcc
	v_cndmask_b32_e32 v200, v200, v202, vcc
	v_mov_b32_e32 v171, v170
	v_mov_b32_e32 v172, v170
	v_mov_b32_e32 v173, v170
	v_mov_b32_e32 v174, v170
	v_mov_b32_e32 v175, v170
	v_mov_b32_e32 v176, v170
	v_mov_b32_e32 v177, v170
	v_mov_b32_e32 v178, v170
	v_mov_b32_e32 v179, v170
	v_mov_b32_e32 v180, v170
	v_mov_b32_e32 v181, v170
	v_mov_b32_e32 v182, v170
	v_mov_b32_e32 v183, v170
	v_mov_b32_e32 v184, v170
	v_mov_b32_e32 v185, v170
	v_mul_f32_e32 v166, v166, v196
	v_mul_f32_e32 v18, v18, v196
	v_mul_f32_e32 v19, v19, v196
	v_mul_f32_e32 v20, v20, v196
	v_mul_f32_e32 v21, v21, v196
	v_mul_f32_e32 v22, v22, v196
	v_mul_f32_e32 v23, v23, v196
	v_mul_f32_e32 v24, v24, v196
	v_mul_f32_e32 v25, v25, v196
	v_mul_f32_e32 v26, v26, v196
	v_mul_f32_e32 v27, v27, v196
	v_mul_f32_e32 v28, v28, v196
	v_mul_f32_e32 v29, v29, v196
	v_mul_f32_e32 v30, v30, v196
	v_mul_f32_e32 v31, v31, v196
	v_mul_f32_e32 v32, v32, v196
	v_mul_f32_e32 v33, v33, v196
	v_mul_f32_e32 v2, v2, v196
	v_mul_f32_e32 v3, v3, v196
	v_mul_f32_e32 v4, v4, v196
	v_mul_f32_e32 v5, v5, v196
	v_mul_f32_e32 v6, v6, v196
	v_mul_f32_e32 v7, v7, v196
	v_mul_f32_e32 v8, v8, v196
	v_mul_f32_e32 v9, v9, v196
	v_mul_f32_e32 v10, v10, v196
	v_mul_f32_e32 v11, v11, v196
	v_mul_f32_e32 v12, v12, v196
	v_mul_f32_e32 v13, v13, v196
	v_mul_f32_e32 v14, v14, v196
	v_mul_f32_e32 v15, v15, v196
	v_mul_f32_e32 v16, v16, v196
	v_mul_f32_e32 v17, v17, v196
	v_sub_f32_e32 v34, v34, v199
	v_sub_f32_e32 v35, v35, v199
	v_sub_f32_e32 v36, v36, v199
	v_sub_f32_e32 v37, v37, v199
	v_sub_f32_e32 v38, v38, v199
	v_sub_f32_e32 v39, v39, v199
	v_sub_f32_e32 v40, v40, v199
	v_sub_f32_e32 v41, v41, v199
	v_sub_f32_e32 v42, v42, v199
	v_sub_f32_e32 v43, v43, v199
	v_sub_f32_e32 v44, v44, v199
	v_sub_f32_e32 v45, v45, v199
	v_sub_f32_e32 v46, v46, v199
	v_sub_f32_e32 v47, v47, v199
	v_sub_f32_e32 v48, v48, v199
	v_sub_f32_e32 v49, v49, v199
	s_branch .Lwin_noupd_A
.Lwin_edge_B:
	v_add_u32_e32 v199, s10, v201
	v_cmp_gt_u32_e32 vcc, 0x200, v199
	s_nop 1
	v_cndmask_b32_e32 v34, v249, v170, vcc
	v_add_u32_e32 v198, 1, v199
	v_cmp_gt_u32_e32 vcc, 0x200, v198
	s_nop 1
	v_cndmask_b32_e32 v35, v249, v170, vcc
	v_add_u32_e32 v198, 2, v199
	v_cmp_gt_u32_e32 vcc, 0x200, v198
	s_nop 1
	v_cndmask_b32_e32 v36, v249, v170, vcc
	v_add_u32_e32 v198, 3, v199
	v_cmp_gt_u32_e32 vcc, 0x200, v198
	s_nop 1
	v_cndmask_b32_e32 v37, v249, v170, vcc
	v_add_u32_e32 v198, 4, v199
	v_cmp_gt_u32_e32 vcc, 0x200, v198
	s_nop 1
	v_cndmask_b32_e32 v38, v249, v170, vcc
	v_add_u32_e32 v198, 5, v199
	v_cmp_gt_u32_e32 vcc, 0x200, v198
	s_nop 1
	v_cndmask_b32_e32 v39, v249, v170, vcc
	v_add_u32_e32 v198, 6, v199
	v_cmp_gt_u32_e32 vcc, 0x200, v198
	s_nop 1
	v_cndmask_b32_e32 v40, v249, v170, vcc
	v_add_u32_e32 v198, 7, v199
	v_cmp_gt_u32_e32 vcc, 0x200, v198
	s_nop 1
	v_cndmask_b32_e32 v41, v249, v170, vcc
	v_add_u32_e32 v198, 16, v199
	v_cmp_gt_u32_e32 vcc, 0x200, v198
	s_nop 1
	v_cndmask_b32_e32 v42, v249, v170, vcc
	v_add_u32_e32 v198, 17, v199
	v_cmp_gt_u32_e32 vcc, 0x200, v198
	s_nop 1
	v_cndmask_b32_e32 v43, v249, v170, vcc
	v_add_u32_e32 v198, 18, v199
	v_cmp_gt_u32_e32 vcc, 0x200, v198
	s_nop 1
	v_cndmask_b32_e32 v44, v249, v170, vcc
	v_add_u32_e32 v198, 19, v199
	v_cmp_gt_u32_e32 vcc, 0x200, v198
	s_nop 1
	v_cndmask_b32_e32 v45, v249, v170, vcc
	v_add_u32_e32 v198, 20, v199
	v_cmp_gt_u32_e32 vcc, 0x200, v198
	s_nop 1
	v_cndmask_b32_e32 v46, v249, v170, vcc
	v_add_u32_e32 v198, 21, v199
	v_cmp_gt_u32_e32 vcc, 0x200, v198
	s_nop 1
	v_cndmask_b32_e32 v47, v249, v170, vcc
	v_add_u32_e32 v198, 22, v199
	v_cmp_gt_u32_e32 vcc, 0x200, v198
	s_nop 1
	v_cndmask_b32_e32 v48, v249, v170, vcc
	v_add_u32_e32 v198, 23, v199
	v_cmp_gt_u32_e32 vcc, 0x200, v198
	s_nop 1
	v_cndmask_b32_e32 v49, v249, v170, vcc
	s_nop 1
	v_mfma_f32_32x32x16_bf16 v[34:49], v[98:101], v[50:53], v[34:49]
	s_branch .Lwin_qk_B

; __device__ __forceinline__ f32x16 mfma32(bf16x8 a, bf16x8 b, f32x16 c) { return __builtin_amdgcn_mfma_f32_32x32x16_bf16(a, b, c, 0, 0, 0); }
; __device__ __forceinline__ void flash_compute(bool domask, const bf16x8 (&kf)[4], const bf16x8 (&vf)[4], const bf16x8 (&q)[4], int x0, unsigned span, float& m, float& l, f32x16 (&O)[2]) {
;     ...
;     for (int s = 0; s < 4; ++s) sc = mfma32(kf[s], q[s], sc);
;     __builtin_amdgcn_s_setprio(0);
;     if (domask) {
; #pragma unroll
;         for (int i = 0; i < 16; ++i) sc[i] = ((unsigned)(x0 + i + (i >= 8 ? 8 : 0)) <= span) ? sc[i] : -1e30f;
;     }
.Lwin_edge_C:
	v_add_u32_e32 v199, s10, v201
	v_cmp_gt_u32_e32 vcc, 0x200, v199
	s_nop 1
	v_cndmask_b32_e32 v34, v249, v170, vcc
	v_add_u32_e32 v198, 1, v199
	v_cmp_gt_u32_e32 vcc, 0x200, v198
	s_nop 1
	v_cndmask_b32_e32 v35, v249, v170, vcc
	v_add_u32_e32 v198, 2, v199
	v_cmp_gt_u32_e32 vcc, 0x200, v198
	s_nop 1
	v_cndmask_b32_e32 v36, v249, v170, vcc
	v_add_u32_e32 v198, 3, v199
	v_cmp_gt_u32_e32 vcc, 0x200, v198
	s_nop 1
	v_cndmask_b32_e32 v37, v249, v170, vcc
	v_add_u32_e32 v198, 4, v199
	v_cmp_gt_u32_e32 vcc, 0x200, v198
	s_nop 1
	v_cndmask_b32_e32 v38, v249, v170, vcc
	v_add_u32_e32 v198, 5, v199
	v_cmp_gt_u32_e32 vcc, 0x200, v198
	s_nop 1
	v_cndmask_b32_e32 v39, v249, v170, vcc
	v_add_u32_e32 v198, 6, v199
	v_cmp_gt_u32_e32 vcc, 0x200, v198
	s_nop 1
	v_cndmask_b32_e32 v40, v249, v170, vcc
	v_add_u32_e32 v198, 7, v199
	v_cmp_gt_u32_e32 vcc, 0x200, v198
	s_nop 1
	v_cndmask_b32_e32 v41, v249, v170, vcc
	v_add_u32_e32 v198, 16, v199
	v_cmp_gt_u32_e32 vcc, 0x200, v198
	s_nop 1
	v_cndmask_b32_e32 v42, v249, v170, vcc
	v_add_u32_e32 v198, 17, v199
	v_cmp_gt_u32_e32 vcc, 0x200, v198
	s_nop 1
	v_cndmask_b32_e32 v43, v249, v170, vcc
	v_add_u32_e32 v198, 18, v199
	v_cmp_gt_u32_e32 vcc, 0x200, v198
	s_nop 1
	v_cndmask_b32_e32 v44, v249, v170, vcc
	v_add_u32_e32 v198, 19, v199
	v_cmp_gt_u32_e32 vcc, 0x200, v198
	s_nop 1
	v_cndmask_b32_e32 v45, v249, v170, vcc
	v_add_u32_e32 v198, 20, v199
	v_cmp_gt_u32_e32 vcc, 0x200, v198
	s_nop 1
	v_cndmask_b32_e32 v46, v249, v170, vcc
	v_add_u32_e32 v198, 21, v199
	v_cmp_gt_u32_e32 vcc, 0x200, v198
	s_nop 1
	v_cndmask_b32_e32 v47, v249, v170, vcc
	v_add_u32_e32 v198, 22, v199
	v_cmp_gt_u32_e32 vcc, 0x200, v198
	s_nop 1
	v_cndmask_b32_e32 v48, v249, v170, vcc
	v_add_u32_e32 v198, 23, v199
	v_cmp_gt_u32_e32 vcc, 0x200, v198
	s_nop 1
	v_cndmask_b32_e32 v49, v249, v170, vcc
	s_nop 1
	v_mfma_f32_32x32x16_bf16 v[34:49], v[130:133], v[50:53], v[34:49]
	s_branch .Lwin_qk_C
